# attention: waves 4-7 run finishSM before QK^T (ping-pong clone) + K-fragment reads kept 3-4 ahead of the QK^T MFMAs, on v021
# speedup vs baseline: 1.0044x; 1.0014x over previous
.LBB0_738:
	s_cmp_lt_u32 s78, 4
	s_cbranch_scc0 .Latt1_738
	s_add_i32 s2, s26, -1
	ds_read_b128 v[64:67], v170 offset:49152
	ds_read_b128 v[68:71], v170 offset:57344
	ds_read_b128 v[154:157], v171 offset:49152
	ds_read_b128 v[190:193], v171 offset:57344
	ds_read_b128 v[202:205], v172 offset:49152
	ds_read_b128 v[224:227], v172 offset:57344
	s_add_i32 s3, 0, 0x12000
	v_add_u32_e32 v189, s3, v178
	s_cmp_gt_u32 s2, s27
	s_cselect_b64 vcc, -1, 0
	s_waitcnt lgkmcnt(5)
	v_mfma_f32_32x32x16_bf16 v[80:95], v[64:67], v[126:129], 0
	s_waitcnt lgkmcnt(4)
	v_mfma_f32_32x32x16_bf16 v[64:79], v[68:71], v[126:129], 0
	s_waitcnt lgkmcnt(3)
	v_mfma_f32_32x32x16_bf16 v[80:95], v[154:157], v[122:125], v[80:95]
	ds_read_b128 v[154:157], v173 offset:49152
	s_waitcnt lgkmcnt(3)
	v_mfma_f32_32x32x16_bf16 v[64:79], v[190:193], v[122:125], v[64:79]
	ds_read_b128 v[190:193], v173 offset:57344
	s_waitcnt lgkmcnt(3)
	v_mfma_f32_32x32x16_bf16 v[80:95], v[202:205], v[118:121], v[80:95]
	ds_read_b128 v[202:205], v174 offset:49152
	s_waitcnt lgkmcnt(3)
	v_mfma_f32_32x32x16_bf16 v[64:79], v[224:227], v[118:121], v[64:79]
	ds_read_b128 v[224:227], v174 offset:57344
	s_waitcnt lgkmcnt(3)
	v_mfma_f32_32x32x16_bf16 v[80:95], v[154:157], v[114:117], v[80:95]
	ds_read_b128 v[154:157], v175 offset:49152
	s_waitcnt lgkmcnt(3)
	v_mfma_f32_32x32x16_bf16 v[64:79], v[190:193], v[114:117], v[64:79]
	ds_read_b128 v[190:193], v175 offset:57344
	s_waitcnt lgkmcnt(3)
	v_mfma_f32_32x32x16_bf16 v[80:95], v[202:205], v[110:113], v[80:95]
	ds_read_b128 v[202:205], v176 offset:49152
	s_waitcnt lgkmcnt(3)
	v_mfma_f32_32x32x16_bf16 v[64:79], v[224:227], v[110:113], v[64:79]
	ds_read_b128 v[224:227], v176 offset:57344
	s_waitcnt lgkmcnt(3)
	v_mfma_f32_32x32x16_bf16 v[80:95], v[154:157], v[106:109], v[80:95]
	ds_read_b128 v[154:157], v177 offset:49152
	s_waitcnt lgkmcnt(3)
	v_mfma_f32_32x32x16_bf16 v[64:79], v[190:193], v[106:109], v[64:79]
	ds_read_b128 v[190:193], v177 offset:57344
	s_waitcnt lgkmcnt(3)
	v_mfma_f32_32x32x16_bf16 v[80:95], v[202:205], v[102:105], v[80:95]
	s_waitcnt lgkmcnt(2)
	v_mfma_f32_32x32x16_bf16 v[64:79], v[224:227], v[102:105], v[64:79]
	s_waitcnt lgkmcnt(1)
	v_mfma_f32_32x32x16_bf16 v[80:95], v[154:157], v[98:101], v[80:95]
	s_waitcnt lgkmcnt(0)
	v_mfma_f32_32x32x16_bf16 v[64:79], v[190:193], v[98:101], v[64:79]
	ds_read_b128 v[154:157], v189
	ds_read_b128 v[190:193], v189 offset:4096
	ds_read_b128 v[202:205], v163
	s_waitcnt lgkmcnt(0)
	v_mfma_f32_32x32x16_bf16 v[80:95], v[154:157], v[202:205], v[80:95]
	v_mfma_f32_32x32x16_bf16 v[64:79], v[190:193], v[202:205], v[64:79]
	v_add_u32_e32 v190, s3, v180
	ds_read_b128 v[154:157], v190
	ds_read_b128 v[192:195], v190 offset:4096
	ds_read_b128 v[202:205], v163 offset:1024
	v_add_u32_e32 v191, s3, v182
	s_waitcnt lgkmcnt(0)
	v_mfma_f32_32x32x16_bf16 v[80:95], v[154:157], v[202:205], v[80:95]
	v_mfma_f32_32x32x16_bf16 v[64:79], v[192:195], v[202:205], v[64:79]
	ds_read_b128 v[154:157], v191
	ds_read_b128 v[192:195], v191 offset:4096
	ds_read_b128 v[202:205], v163 offset:2048
	s_waitcnt lgkmcnt(0)
	v_mfma_f32_32x32x16_bf16 v[80:95], v[154:157], v[202:205], v[80:95]
	v_mfma_f32_32x32x16_bf16 v[64:79], v[192:195], v[202:205], v[64:79]
	v_add_u32_e32 v192, s3, v184
	ds_read_b128 v[154:157], v192
	ds_read_b128 v[202:205], v192 offset:4096
	ds_read_b128 v[224:227], v163 offset:3072
	s_waitcnt lgkmcnt(0)
	v_mfma_f32_32x32x16_bf16 v[80:95], v[154:157], v[224:227], v[80:95]
	v_mfma_f32_32x32x16_bf16 v[64:79], v[202:205], v[224:227], v[64:79]
	s_nop 10
	v_cndmask_b32_e32 v240, v80, v208, vcc
	v_add_f32_e32 v80, 0, v220
	v_add_f32_e32 v80, v222, v80
	v_add_f32_e32 v80, v218, v80
	v_add_f32_e32 v80, v221, v80
	v_add_f32_e32 v80, v216, v80
	v_add_f32_e32 v80, v219, v80
	v_add_f32_e32 v80, v215, v80
	v_add_f32_e32 v80, v217, v80
	v_add_f32_e32 v80, v212, v80
	v_add_f32_e32 v80, v214, v80
	v_add_f32_e32 v80, v210, v80
	v_add_f32_e32 v80, v213, v80
	v_cndmask_b32_e32 v244, v64, v208, vcc
	v_exp_f32_e32 v64, v148
	v_add_f32_e32 v80, v198, v80
	v_cndmask_b32_e32 v245, v65, v208, vcc
	v_exp_f32_e32 v65, v149
	v_add_f32_e32 v80, v211, v80
	v_cndmask_b32_e32 v242, v66, v208, vcc
	v_exp_f32_e32 v66, v146
	v_add_f32_e32 v80, v197, v80
	v_cndmask_b32_e32 v243, v67, v208, vcc
	v_exp_f32_e32 v67, v147
	v_add_f32_e32 v80, v199, v80
	v_cndmask_b32_e32 v238, v68, v208, vcc
	v_exp_f32_e32 v68, v144
	v_add_f32_e32 v80, v64, v80
	v_cndmask_b32_e32 v239, v69, v208, vcc
	v_exp_f32_e32 v69, v145
	v_add_f32_e32 v80, v65, v80
	v_cndmask_b32_e32 v234, v70, v208, vcc
	v_exp_f32_e32 v70, v140
	v_add_f32_e32 v80, v66, v80
	v_cndmask_b32_e32 v235, v71, v208, vcc
	v_exp_f32_e32 v71, v141
	v_add_f32_e32 v80, v67, v80
	v_cndmask_b32_e32 v230, v72, v208, vcc
	v_exp_f32_e32 v72, v138
	v_add_f32_e32 v80, v68, v80
	v_cndmask_b32_e32 v231, v73, v208, vcc
	v_exp_f32_e32 v73, v139
	v_add_f32_e32 v80, v69, v80
	v_cndmask_b32_e32 v227, v74, v208, vcc
	v_exp_f32_e32 v74, v152
	v_add_f32_e32 v80, v70, v80
	v_cndmask_b32_e32 v228, v75, v208, vcc
	v_exp_f32_e32 v75, v153
	v_add_f32_e32 v80, v71, v80
	v_cndmask_b32_e32 v225, v76, v208, vcc
	v_exp_f32_e32 v76, v150
	v_add_f32_e32 v80, v72, v80
	v_cndmask_b32_e32 v195, v90, v208, vcc
	v_cndmask_b32_e32 v90, v77, v208, vcc
	v_exp_f32_e32 v77, v151
	v_add_f32_e32 v80, v73, v80
	v_cndmask_b32_e32 v223, v88, v208, vcc
	v_cndmask_b32_e32 v88, v78, v208, vcc
	v_exp_f32_e32 v78, v142
	v_add_f32_e32 v80, v74, v80
	v_cndmask_b32_e32 v224, v89, v208, vcc
	v_cndmask_b32_e32 v89, v79, v208, vcc
	v_exp_f32_e32 v79, v143
	v_add_f32_e32 v80, v75, v80
	v_add_f32_e32 v80, v76, v80
	v_add_f32_e32 v80, v77, v80
	v_add_f32_e32 v80, v78, v80
	v_add_f32_e32 v193, v79, v80
	v_cndmask_b32_e32 v226, v86, v208, vcc
	v_cndmask_b32_e32 v232, v84, v208, vcc
	v_cndmask_b32_e32 v233, v85, v208, vcc
	v_mov_b32_e32 v194, v193
	v_cvt_pk_bf16_f32 v84, v220, v222
	v_cvt_pk_bf16_f32 v85, v218, v221
	v_cvt_pk_bf16_f32 v86, v216, v219
	v_cndmask_b32_e32 v94, v94, v208, vcc
	v_cndmask_b32_e32 v95, v95, v208, vcc
	v_cndmask_b32_e32 v92, v92, v208, vcc
	v_cndmask_b32_e32 v93, v93, v208, vcc
	v_cndmask_b32_e32 v91, v91, v208, vcc
	v_cndmask_b32_e32 v229, v87, v208, vcc
	v_cndmask_b32_e32 v236, v82, v208, vcc
	v_cndmask_b32_e32 v237, v83, v208, vcc
	v_cndmask_b32_e32 v241, v81, v208, vcc
	v_permlane32_swap_b32_e32 v193, v194
	v_cvt_pk_bf16_f32 v87, v215, v217
	v_permlane32_swap_b32_e32 v84, v86
	v_cvt_pk_bf16_f32 v142, v212, v214
	v_cvt_pk_bf16_f32 v143, v210, v213
	v_cvt_pk_bf16_f32 v144, v198, v211
	v_cvt_pk_bf16_f32 v145, v197, v199
	v_cvt_pk_bf16_f32 v146, v64, v65
	v_cvt_pk_bf16_f32 v147, v66, v67
	v_cvt_pk_bf16_f32 v148, v68, v69
	v_cvt_pk_bf16_f32 v149, v70, v71
	v_cvt_pk_bf16_f32 v150, v72, v73
	v_cvt_pk_bf16_f32 v151, v74, v75
	v_cvt_pk_bf16_f32 v152, v76, v77
	v_cvt_pk_bf16_f32 v153, v78, v79
	v_permlane32_swap_b32_e32 v85, v87
	v_permlane32_swap_b32_e32 v142, v144
	v_permlane32_swap_b32_e32 v143, v145
	v_permlane32_swap_b32_e32 v146, v148
	v_permlane32_swap_b32_e32 v147, v149
	v_permlane32_swap_b32_e32 v150, v152
	v_permlane32_swap_b32_e32 v151, v153
	v_lshl_add_u64 v[138:139], v[134:135], 0, s[0:1]
	s_mov_b32 s3, 0x33080000
	v_add_co_u32_e32 v68, vcc, s3, v138
	s_mov_b32 s3, 0x330a0000
	s_nop 0
	v_addc_co_u32_e32 v69, vcc, 0, v139, vcc
	v_add_co_u32_e32 v72, vcc, s3, v138
	v_lshl_add_u64 v[140:141], v[132:133], 0, s[0:1]
	s_nop 0
	v_addc_co_u32_e32 v73, vcc, 0, v139, vcc
	s_mov_b32 s3, 0x2f804000
	global_load_dwordx4 v[64:67], v[68:69], off offset:256
	s_nop 0
	global_load_dwordx4 v[68:71], v[68:69], off
	s_nop 0
	global_load_dwordx4 v[76:79], v[72:73], off offset:256
	s_nop 0
	global_load_dwordx4 v[72:75], v[72:73], off
	v_add_co_u32_e32 v80, vcc, s3, v140
	s_nop 1
	v_addc_co_u32_e32 v81, vcc, 0, v141, vcc
	global_load_dwordx4 v[80:83], v[80:81], off
	ds_read_b64_tr_b16 v[154:155], v164 offset:0
	ds_read_b64_tr_b16 v[156:157], v164 offset:0x800
	ds_read_b64_tr_b16 v[196:197], v164 offset:0x1000
	ds_read_b64_tr_b16 v[198:199], v164 offset:0x1800
	ds_read_b64_tr_b16 v[202:203], v164 offset:0x2000
	ds_read_b64_tr_b16 v[204:205], v164 offset:0x2800
	ds_read_b64_tr_b16 v[210:211], v164 offset:0x3000
	ds_read_b64_tr_b16 v[212:213], v164 offset:0x3800
	s_waitcnt lgkmcnt(0)
	s_nop 0
	v_mfma_f32_32x32x16_bf16 v[0:15], v[84:87], v[154:157], v[0:15]
	ds_read_b64_tr_b16 v[154:155], v164 offset:0x200
	ds_read_b64_tr_b16 v[156:157], v164 offset:0xa00
	v_mfma_f32_32x32x16_bf16 v[0:15], v[142:145], v[196:199], v[0:15]
	ds_read_b64_tr_b16 v[196:197], v164 offset:0x1200
	ds_read_b64_tr_b16 v[198:199], v164 offset:0x1a00
	v_mfma_f32_32x32x16_bf16 v[0:15], v[146:149], v[202:205], v[0:15]
	ds_read_b64_tr_b16 v[202:203], v164 offset:0x2200
	ds_read_b64_tr_b16 v[204:205], v164 offset:0x2a00
	v_mfma_f32_32x32x16_bf16 v[0:15], v[150:153], v[210:213], v[0:15]
	ds_read_b64_tr_b16 v[210:211], v164 offset:0x3200
	ds_read_b64_tr_b16 v[212:213], v164 offset:0x3a00
	s_waitcnt lgkmcnt(0)
	v_mfma_f32_32x32x16_bf16 v[48:63], v[84:87], v[154:157], v[48:63]
	ds_read_b64_tr_b16 v[154:155], v164 offset:0x400
	ds_read_b64_tr_b16 v[156:157], v164 offset:0xc00
	v_mfma_f32_32x32x16_bf16 v[48:63], v[142:145], v[196:199], v[48:63]
	ds_read_b64_tr_b16 v[196:197], v164 offset:0x1400
	ds_read_b64_tr_b16 v[198:199], v164 offset:0x1c00
	v_mfma_f32_32x32x16_bf16 v[48:63], v[146:149], v[202:205], v[48:63]
	ds_read_b64_tr_b16 v[202:203], v164 offset:0x2400
	ds_read_b64_tr_b16 v[204:205], v164 offset:0x2c00
	v_mfma_f32_32x32x16_bf16 v[48:63], v[150:153], v[210:213], v[48:63]
	ds_read_b64_tr_b16 v[210:211], v164 offset:0x3400
	ds_read_b64_tr_b16 v[212:213], v164 offset:0x3c00
	s_waitcnt lgkmcnt(0)
	v_mfma_f32_32x32x16_bf16 v[32:47], v[84:87], v[154:157], v[32:47]
	ds_read_b64_tr_b16 v[154:155], v164 offset:0x600
	ds_read_b64_tr_b16 v[156:157], v164 offset:0xe00
	v_mfma_f32_32x32x16_bf16 v[32:47], v[142:145], v[196:199], v[32:47]
	ds_read_b64_tr_b16 v[196:197], v164 offset:0x1600
	ds_read_b64_tr_b16 v[198:199], v164 offset:0x1e00
	v_mfma_f32_32x32x16_bf16 v[32:47], v[146:149], v[202:205], v[32:47]
	ds_read_b64_tr_b16 v[202:203], v164 offset:0x2600
	ds_read_b64_tr_b16 v[204:205], v164 offset:0x2e00
	v_mfma_f32_32x32x16_bf16 v[32:47], v[150:153], v[210:213], v[32:47]
	ds_read_b64_tr_b16 v[210:211], v164 offset:0x3600
	ds_read_b64_tr_b16 v[212:213], v164 offset:0x3e00
	s_waitcnt lgkmcnt(0)
	v_mfma_f32_32x32x16_bf16 v[16:31], v[84:87], v[154:157], v[16:31]
	v_max_f32_e32 v84, v241, v241
	v_max_f32_e32 v85, v240, v240
	v_max_f32_e32 v84, v85, v84
	v_max3_f32 v84, v84, v236, v237
	v_max3_f32 v84, v84, v232, v233
	v_max3_f32 v84, v84, v226, v229
	v_max3_f32 v84, v84, v223, v224
	v_mfma_f32_32x32x16_bf16 v[16:31], v[142:145], v[196:199], v[16:31]
	v_max3_f32 v84, v84, v195, v91
	v_max3_f32 v84, v84, v92, v93
	v_max3_f32 v84, v84, v94, v95
	v_max3_f32 v84, v84, v244, v245
	v_max3_f32 v84, v84, v242, v243
	v_max3_f32 v84, v84, v238, v239
	v_max3_f32 v84, v84, v234, v235
	v_mfma_f32_32x32x16_bf16 v[16:31], v[146:149], v[202:205], v[16:31]
	v_max3_f32 v84, v84, v230, v231
	v_max3_f32 v84, v84, v227, v228
	v_max3_f32 v84, v84, v225, v90
	v_max3_f32 v84, v84, v88, v89
	v_mov_b32_e32 v85, v84
	s_nop 1
	v_permlane32_swap_b32_e32 v84, v85
	v_mfma_f32_32x32x16_bf16 v[16:31], v[150:153], v[210:213], v[16:31]
	v_max_f32_e32 v85, v85, v85
	v_max_f32_e32 v84, v84, v84
	v_max_f32_e32 v84, v84, v85
	v_sub_f32_e32 v85, v84, v165
	v_cmp_ge_f32_e32 vcc, s21, v85
	v_mov_b32_e32 v196, 1.0
	s_cmp_eq_u64 vcc, exec
	s_cbranch_scc0 .LBB0_750

.LBB0_743:
	v_mul_f32_e32 v136, 0xbdd53b94, v165
	v_fmamk_f32 v78, v94, 0x3dd53b94, v136
	v_fmamk_f32 v74, v195, 0x3dd53b94, v136
	v_exp_f32_e32 v195, v78
	v_fmamk_f32 v64, v240, 0x3dd53b94, v136
	v_fmamk_f32 v65, v241, 0x3dd53b94, v136
	v_fmamk_f32 v66, v236, 0x3dd53b94, v136
	v_fmamk_f32 v67, v237, 0x3dd53b94, v136
	v_fmamk_f32 v68, v232, 0x3dd53b94, v136
	v_fmamk_f32 v69, v233, 0x3dd53b94, v136
	v_fmamk_f32 v70, v226, 0x3dd53b94, v136
	v_fmamk_f32 v71, v229, 0x3dd53b94, v136
	v_fmamk_f32 v72, v223, 0x3dd53b94, v136
	v_fmamk_f32 v73, v224, 0x3dd53b94, v136
	v_fmamk_f32 v75, v91, 0x3dd53b94, v136
	v_fmamk_f32 v76, v92, 0x3dd53b94, v136
	v_fmamk_f32 v77, v93, 0x3dd53b94, v136
	v_fmamk_f32 v79, v95, 0x3dd53b94, v136
	v_fmamk_f32 v223, v244, 0x3dd53b94, v136
	v_fmamk_f32 v224, v245, 0x3dd53b94, v136
	v_fmamk_f32 v236, v242, 0x3dd53b94, v136
	v_fmamk_f32 v237, v243, 0x3dd53b94, v136
	v_fmamk_f32 v238, v238, 0x3dd53b94, v136
	v_fmamk_f32 v239, v239, 0x3dd53b94, v136
	v_fmamk_f32 v240, v234, 0x3dd53b94, v136
	v_fmamk_f32 v241, v235, 0x3dd53b94, v136
	v_fmamk_f32 v242, v230, 0x3dd53b94, v136
	v_fmamk_f32 v243, v231, 0x3dd53b94, v136
	v_fmamk_f32 v244, v227, 0x3dd53b94, v136
	v_fmamk_f32 v245, v228, 0x3dd53b94, v136
	v_fmamk_f32 v246, v225, 0x3dd53b94, v136
	v_exp_f32_e32 v233, v64
	v_exp_f32_e32 v235, v65
	v_exp_f32_e32 v231, v66
	v_exp_f32_e32 v234, v67
	v_exp_f32_e32 v229, v68
	v_exp_f32_e32 v232, v69
	v_exp_f32_e32 v228, v70
	v_exp_f32_e32 v230, v71
	v_exp_f32_e32 v225, v72
	v_exp_f32_e32 v227, v73
	v_exp_f32_e32 v221, v74
	v_exp_f32_e32 v226, v75
	v_exp_f32_e32 v219, v76
	v_exp_f32_e32 v222, v77
	v_exp_f32_e32 v220, v79
	v_fmamk_f32 v247, v90, 0x3dd53b94, v136
	v_fmamk_f32 v248, v88, 0x3dd53b94, v136
	v_fmamk_f32 v202, v89, 0x3dd53b94, v136
	s_waitcnt lgkmcnt(0)
	s_barrier
	ds_read_b128 v[64:67], v170 offset:32768
	ds_read_b128 v[68:71], v170 offset:40960
	ds_read_b128 v[142:145], v171 offset:32768
	ds_read_b128 v[146:149], v171 offset:40960
	ds_read_b128 v[150:153], v172 offset:32768
	s_cmp_lt_u32 s2, s27
	s_cselect_b64 vcc, -1, 0
	s_waitcnt lgkmcnt(4)
	v_mfma_f32_32x32x16_bf16 v[80:95], v[64:67], v[126:129], 0
	s_waitcnt lgkmcnt(3)
	v_mfma_f32_32x32x16_bf16 v[64:79], v[68:71], v[126:129], 0
	s_waitcnt lgkmcnt(2)
	v_mfma_f32_32x32x16_bf16 v[80:95], v[142:145], v[122:125], v[80:95]
	ds_read_b128 v[142:145], v172 offset:40960
	s_waitcnt lgkmcnt(2)
	v_mfma_f32_32x32x16_bf16 v[64:79], v[146:149], v[122:125], v[64:79]
	ds_read_b128 v[146:149], v173 offset:32768
	s_waitcnt lgkmcnt(2)
	v_mfma_f32_32x32x16_bf16 v[80:95], v[150:153], v[118:121], v[80:95]
	ds_read_b128 v[150:153], v173 offset:40960
	s_waitcnt lgkmcnt(2)
	v_mfma_f32_32x32x16_bf16 v[64:79], v[142:145], v[118:121], v[64:79]
	ds_read_b128 v[142:145], v174 offset:32768
	s_waitcnt lgkmcnt(2)
	v_mfma_f32_32x32x16_bf16 v[80:95], v[146:149], v[114:117], v[80:95]
	ds_read_b128 v[146:149], v174 offset:40960
	s_waitcnt lgkmcnt(2)
	v_mfma_f32_32x32x16_bf16 v[64:79], v[150:153], v[114:117], v[64:79]
	ds_read_b128 v[150:153], v175 offset:32768
	s_waitcnt lgkmcnt(2)
	v_mfma_f32_32x32x16_bf16 v[80:95], v[142:145], v[110:113], v[80:95]
	ds_read_b128 v[142:145], v175 offset:40960
	s_waitcnt lgkmcnt(2)
	v_mfma_f32_32x32x16_bf16 v[64:79], v[146:149], v[110:113], v[64:79]
	ds_read_b128 v[146:149], v176 offset:32768
	s_waitcnt lgkmcnt(2)
	v_mfma_f32_32x32x16_bf16 v[80:95], v[150:153], v[106:109], v[80:95]
	ds_read_b128 v[150:153], v176 offset:40960
	s_waitcnt lgkmcnt(2)
	v_mfma_f32_32x32x16_bf16 v[64:79], v[142:145], v[106:109], v[64:79]
	ds_read_b128 v[142:145], v177 offset:32768
	s_waitcnt lgkmcnt(2)
	v_mfma_f32_32x32x16_bf16 v[80:95], v[146:149], v[102:105], v[80:95]
	ds_read_b128 v[146:149], v177 offset:40960
	s_waitcnt lgkmcnt(2)
	v_mfma_f32_32x32x16_bf16 v[64:79], v[150:153], v[102:105], v[64:79]
	s_waitcnt lgkmcnt(1)
	v_mfma_f32_32x32x16_bf16 v[80:95], v[142:145], v[98:101], v[80:95]
	s_waitcnt lgkmcnt(0)
	v_mfma_f32_32x32x16_bf16 v[64:79], v[146:149], v[98:101], v[64:79]
	ds_read_b128 v[142:145], v179
	ds_read_b128 v[146:149], v179 offset:4096
	ds_read_b128 v[150:153], v163
	s_waitcnt lgkmcnt(0)
	v_mfma_f32_32x32x16_bf16 v[80:95], v[142:145], v[150:153], v[80:95]
	v_mfma_f32_32x32x16_bf16 v[64:79], v[146:149], v[150:153], v[64:79]
	ds_read_b128 v[142:145], v181
	ds_read_b128 v[146:149], v181 offset:4096
	ds_read_b128 v[150:153], v163 offset:1024
	s_waitcnt lgkmcnt(0)
	v_mfma_f32_32x32x16_bf16 v[80:95], v[142:145], v[150:153], v[80:95]
	v_mfma_f32_32x32x16_bf16 v[64:79], v[146:149], v[150:153], v[64:79]
	ds_read_b128 v[142:145], v183
	ds_read_b128 v[146:149], v183 offset:4096
	ds_read_b128 v[150:153], v163 offset:2048
	s_waitcnt lgkmcnt(0)
	v_mfma_f32_32x32x16_bf16 v[80:95], v[142:145], v[150:153], v[80:95]
	v_mfma_f32_32x32x16_bf16 v[64:79], v[146:149], v[150:153], v[64:79]
	ds_read_b128 v[142:145], v185
	ds_read_b128 v[146:149], v185 offset:4096
	ds_read_b128 v[150:153], v163 offset:3072
	s_waitcnt lgkmcnt(0)
	v_mfma_f32_32x32x16_bf16 v[80:95], v[142:145], v[150:153], v[80:95]
	v_mfma_f32_32x32x16_bf16 v[64:79], v[146:149], v[150:153], v[64:79]
	s_nop 10
	v_cndmask_b32_e32 v218, v208, v80, vcc
	v_add_f32_e32 v80, 0, v233
	v_add_f32_e32 v80, v235, v80
	v_add_f32_e32 v80, v231, v80
	v_add_f32_e32 v80, v234, v80
	v_add_f32_e32 v80, v229, v80
	v_add_f32_e32 v80, v232, v80
	v_add_f32_e32 v80, v228, v80
	v_add_f32_e32 v80, v230, v80
	v_add_f32_e32 v80, v225, v80
	v_add_f32_e32 v80, v227, v80
	v_add_f32_e32 v80, v221, v80
	v_add_f32_e32 v80, v226, v80
	v_cndmask_b32_e32 v148, v208, v64, vcc
	v_exp_f32_e32 v64, v223
	v_add_f32_e32 v80, v219, v80
	v_cndmask_b32_e32 v149, v208, v65, vcc
	v_exp_f32_e32 v65, v224
	v_add_f32_e32 v80, v222, v80
	v_cndmask_b32_e32 v146, v208, v66, vcc
	v_exp_f32_e32 v66, v236
	v_add_f32_e32 v80, v195, v80
	v_cndmask_b32_e32 v147, v208, v67, vcc
	v_exp_f32_e32 v67, v237
	v_add_f32_e32 v80, v220, v80
	v_cndmask_b32_e32 v144, v208, v68, vcc
	v_exp_f32_e32 v68, v238
	v_add_f32_e32 v80, v64, v80
	v_cndmask_b32_e32 v145, v208, v69, vcc
	v_exp_f32_e32 v69, v239
	v_add_f32_e32 v80, v65, v80
	v_cndmask_b32_e32 v142, v208, v70, vcc
	v_exp_f32_e32 v70, v240
	v_add_f32_e32 v80, v66, v80
	v_cndmask_b32_e32 v143, v208, v71, vcc
	v_exp_f32_e32 v71, v241
	v_add_f32_e32 v80, v67, v80
	v_cndmask_b32_e32 v151, v208, v94, vcc
	v_cndmask_b32_e32 v94, v208, v72, vcc
	v_exp_f32_e32 v72, v242
	v_add_f32_e32 v80, v68, v80
	v_cndmask_b32_e32 v150, v208, v95, vcc
	v_cndmask_b32_e32 v95, v208, v73, vcc
	v_exp_f32_e32 v73, v243
	v_add_f32_e32 v80, v69, v80
	v_cndmask_b32_e32 v153, v208, v92, vcc
	v_cndmask_b32_e32 v92, v208, v74, vcc
	v_exp_f32_e32 v74, v244
	v_add_f32_e32 v80, v70, v80
	v_cndmask_b32_e32 v152, v208, v93, vcc
	v_cndmask_b32_e32 v93, v208, v75, vcc
	v_exp_f32_e32 v75, v245
	v_add_f32_e32 v80, v71, v80
	v_cndmask_b32_e32 v198, v208, v90, vcc
	v_cndmask_b32_e32 v90, v208, v76, vcc
	v_exp_f32_e32 v76, v246
	v_add_f32_e32 v80, v72, v80
	v_cndmask_b32_e32 v197, v208, v91, vcc
	v_cndmask_b32_e32 v91, v208, v77, vcc
	v_exp_f32_e32 v77, v247
	v_add_f32_e32 v80, v73, v80
	v_cndmask_b32_e32 v210, v208, v88, vcc
	v_cndmask_b32_e32 v88, v208, v78, vcc
	v_exp_f32_e32 v78, v248
	v_add_f32_e32 v80, v74, v80
	v_cndmask_b32_e32 v199, v208, v89, vcc
	v_cndmask_b32_e32 v89, v208, v79, vcc
	v_exp_f32_e32 v79, v202
	v_add_f32_e32 v80, v75, v80
	v_add_f32_e32 v80, v76, v80
	v_add_f32_e32 v80, v77, v80
	v_add_f32_e32 v80, v78, v80
	v_add_f32_e32 v223, v79, v80
	v_cndmask_b32_e32 v212, v208, v86, vcc
	v_cndmask_b32_e32 v213, v208, v85, vcc
	v_cndmask_b32_e32 v214, v208, v84, vcc
	v_mov_b32_e32 v224, v223
	v_cvt_pk_bf16_f32 v84, v233, v235
	v_cvt_pk_bf16_f32 v85, v231, v234
	v_cvt_pk_bf16_f32 v86, v229, v232
	v_cndmask_b32_e32 v211, v208, v87, vcc
	v_cndmask_b32_e32 v215, v208, v83, vcc
	v_cndmask_b32_e32 v216, v208, v82, vcc
	v_cndmask_b32_e32 v217, v208, v81, vcc
	v_permlane32_swap_b32_e32 v223, v224
	v_cvt_pk_bf16_f32 v87, v228, v230
	v_permlane32_swap_b32_e32 v84, v86
	v_cvt_pk_bf16_f32 v154, v225, v227
	v_cvt_pk_bf16_f32 v155, v221, v226
	v_cvt_pk_bf16_f32 v156, v219, v222
	v_cvt_pk_bf16_f32 v157, v195, v220
	v_cvt_pk_bf16_f32 v202, v64, v65
	v_cvt_pk_bf16_f32 v203, v66, v67
	v_cvt_pk_bf16_f32 v204, v68, v69
	v_cvt_pk_bf16_f32 v205, v70, v71
	v_cvt_pk_bf16_f32 v226, v72, v73
	v_cvt_pk_bf16_f32 v227, v74, v75
	v_cvt_pk_bf16_f32 v228, v76, v77
	v_cvt_pk_bf16_f32 v229, v78, v79
	v_permlane32_swap_b32_e32 v85, v87
	v_permlane32_swap_b32_e32 v154, v156
	v_permlane32_swap_b32_e32 v155, v157
	v_permlane32_swap_b32_e32 v202, v204
	v_permlane32_swap_b32_e32 v203, v205
	v_permlane32_swap_b32_e32 v226, v228
	v_permlane32_swap_b32_e32 v227, v229
	v_add_co_u32_e32 v68, vcc, s22, v138
	s_nop 1
	v_addc_co_u32_e32 v69, vcc, 0, v139, vcc
	v_add_co_u32_e32 v72, vcc, s23, v138
	s_nop 1
	v_addc_co_u32_e32 v73, vcc, 0, v139, vcc
	global_load_dwordx4 v[64:67], v[68:69], off offset:256
	s_nop 0
	global_load_dwordx4 v[68:71], v[68:69], off
	s_nop 0
	global_load_dwordx4 v[76:79], v[72:73], off offset:256
	s_nop 0
	global_load_dwordx4 v[72:75], v[72:73], off
	v_add_co_u32_e32 v80, vcc, s29, v140
	s_nop 1
	v_addc_co_u32_e32 v81, vcc, 0, v141, vcc
	global_load_dwordx4 v[80:83], v[80:81], off
	ds_read_b64_tr_b16 v[138:139], v162 offset:0
	ds_read_b64_tr_b16 v[140:141], v162 offset:0x800
	ds_read_b64_tr_b16 v[230:231], v162 offset:0x1000
	ds_read_b64_tr_b16 v[232:233], v162 offset:0x1800
	ds_read_b64_tr_b16 v[234:235], v162 offset:0x2000
	ds_read_b64_tr_b16 v[236:237], v162 offset:0x2800
	ds_read_b64_tr_b16 v[238:239], v162 offset:0x3000
	ds_read_b64_tr_b16 v[240:241], v162 offset:0x3800
	s_waitcnt lgkmcnt(0)
	s_nop 0
	v_mfma_f32_32x32x16_bf16 v[0:15], v[84:87], v[138:141], v[0:15]
	ds_read_b64_tr_b16 v[138:139], v162 offset:0x200
	ds_read_b64_tr_b16 v[140:141], v162 offset:0xa00
	v_mfma_f32_32x32x16_bf16 v[0:15], v[154:157], v[230:233], v[0:15]
	ds_read_b64_tr_b16 v[230:231], v162 offset:0x1200
	ds_read_b64_tr_b16 v[232:233], v162 offset:0x1a00
	v_mfma_f32_32x32x16_bf16 v[0:15], v[202:205], v[234:237], v[0:15]
	ds_read_b64_tr_b16 v[234:235], v162 offset:0x2200
	ds_read_b64_tr_b16 v[236:237], v162 offset:0x2a00
	v_mfma_f32_32x32x16_bf16 v[0:15], v[226:229], v[238:241], v[0:15]
	ds_read_b64_tr_b16 v[238:239], v162 offset:0x3200
	ds_read_b64_tr_b16 v[240:241], v162 offset:0x3a00
	s_waitcnt lgkmcnt(0)
	v_mfma_f32_32x32x16_bf16 v[48:63], v[84:87], v[138:141], v[48:63]
	ds_read_b64_tr_b16 v[138:139], v162 offset:0x400
	ds_read_b64_tr_b16 v[140:141], v162 offset:0xc00
	v_mfma_f32_32x32x16_bf16 v[48:63], v[154:157], v[230:233], v[48:63]
	ds_read_b64_tr_b16 v[230:231], v162 offset:0x1400
	ds_read_b64_tr_b16 v[232:233], v162 offset:0x1c00
	v_mfma_f32_32x32x16_bf16 v[48:63], v[202:205], v[234:237], v[48:63]
	ds_read_b64_tr_b16 v[234:235], v162 offset:0x2400
	ds_read_b64_tr_b16 v[236:237], v162 offset:0x2c00
	v_mfma_f32_32x32x16_bf16 v[48:63], v[226:229], v[238:241], v[48:63]
	ds_read_b64_tr_b16 v[238:239], v162 offset:0x3400
	ds_read_b64_tr_b16 v[240:241], v162 offset:0x3c00
	s_waitcnt lgkmcnt(0)
	v_mfma_f32_32x32x16_bf16 v[32:47], v[84:87], v[138:141], v[32:47]
	ds_read_b64_tr_b16 v[138:139], v162 offset:0x600
	ds_read_b64_tr_b16 v[140:141], v162 offset:0xe00
	v_mfma_f32_32x32x16_bf16 v[32:47], v[154:157], v[230:233], v[32:47]
	ds_read_b64_tr_b16 v[230:231], v162 offset:0x1600
	ds_read_b64_tr_b16 v[232:233], v162 offset:0x1e00
	v_mfma_f32_32x32x16_bf16 v[32:47], v[202:205], v[234:237], v[32:47]
	ds_read_b64_tr_b16 v[234:235], v162 offset:0x2600
	ds_read_b64_tr_b16 v[236:237], v162 offset:0x2e00
	v_mfma_f32_32x32x16_bf16 v[32:47], v[226:229], v[238:241], v[32:47]
	ds_read_b64_tr_b16 v[238:239], v162 offset:0x3600
	ds_read_b64_tr_b16 v[240:241], v162 offset:0x3e00
	s_waitcnt lgkmcnt(0)
	v_mfma_f32_32x32x16_bf16 v[16:31], v[84:87], v[138:141], v[16:31]
	v_max_f32_e32 v84, v217, v217
	v_max_f32_e32 v85, v218, v218
	v_max_f32_e32 v84, v85, v84
	v_max3_f32 v84, v84, v216, v215
	v_max3_f32 v84, v84, v214, v213
	v_max3_f32 v84, v84, v212, v211
	v_max3_f32 v84, v84, v210, v199
	v_mfma_f32_32x32x16_bf16 v[16:31], v[154:157], v[230:233], v[16:31]
	v_max3_f32 v84, v84, v198, v197
	v_max3_f32 v84, v84, v153, v152
	v_max3_f32 v84, v84, v151, v150
	v_max3_f32 v84, v84, v148, v149
	v_max3_f32 v84, v84, v146, v147
	v_max3_f32 v84, v84, v144, v145
	v_max3_f32 v84, v84, v142, v143
	v_mfma_f32_32x32x16_bf16 v[16:31], v[202:205], v[234:237], v[16:31]
	v_max3_f32 v84, v84, v94, v95
	v_max3_f32 v84, v84, v92, v93
	v_max3_f32 v84, v84, v90, v91
	v_max3_f32 v84, v84, v88, v89
	v_mov_b32_e32 v85, v84
	s_nop 1
	v_permlane32_swap_b32_e32 v84, v85
	v_mfma_f32_32x32x16_bf16 v[16:31], v[226:229], v[238:241], v[16:31]
	v_max_f32_e32 v85, v85, v85
	v_max_f32_e32 v84, v84, v84
	v_max_f32_e32 v84, v84, v85
	v_sub_f32_e32 v85, v84, v165
	v_cmp_ge_f32_e32 vcc, s21, v85
	v_mov_b32_e32 v195, 1.0
	s_cmp_eq_u64 vcc, exec
	s_cbranch_scc0 .LBB0_751

.Latt1_738:
	v_add_f32_e32 v80, 0, v220
	v_add_f32_e32 v80, v222, v80
	v_add_f32_e32 v80, v218, v80
	v_add_f32_e32 v80, v221, v80
	v_add_f32_e32 v80, v216, v80
	v_add_f32_e32 v80, v219, v80
	v_add_f32_e32 v80, v215, v80
	v_add_f32_e32 v80, v217, v80
	v_add_f32_e32 v80, v212, v80
	v_add_f32_e32 v80, v214, v80
	v_add_f32_e32 v80, v210, v80
	v_add_f32_e32 v80, v213, v80
	v_exp_f32_e32 v64, v148
	v_add_f32_e32 v80, v198, v80
	v_exp_f32_e32 v65, v149
	v_add_f32_e32 v80, v211, v80
	v_exp_f32_e32 v66, v146
	v_add_f32_e32 v80, v197, v80
	v_exp_f32_e32 v67, v147
	v_add_f32_e32 v80, v199, v80
	v_exp_f32_e32 v68, v144
	v_add_f32_e32 v80, v64, v80
	v_exp_f32_e32 v69, v145
	v_add_f32_e32 v80, v65, v80
	v_exp_f32_e32 v70, v140
	v_add_f32_e32 v80, v66, v80
	v_exp_f32_e32 v71, v141
	v_add_f32_e32 v80, v67, v80
	v_exp_f32_e32 v72, v138
	v_add_f32_e32 v80, v68, v80
	v_exp_f32_e32 v73, v139
	v_add_f32_e32 v80, v69, v80
	v_exp_f32_e32 v74, v152
	v_add_f32_e32 v80, v70, v80
	v_exp_f32_e32 v75, v153
	v_add_f32_e32 v80, v71, v80
	v_exp_f32_e32 v76, v150
	v_add_f32_e32 v80, v72, v80
	v_exp_f32_e32 v77, v151
	v_add_f32_e32 v80, v73, v80
	v_exp_f32_e32 v78, v142
	v_add_f32_e32 v80, v74, v80
	v_exp_f32_e32 v79, v143
	v_add_f32_e32 v80, v75, v80
	v_add_f32_e32 v80, v76, v80
	v_add_f32_e32 v80, v77, v80
	v_add_f32_e32 v80, v78, v80
	v_add_f32_e32 v246, v79, v80
	v_cvt_pk_bf16_f32 v142, v212, v214
	v_cvt_pk_bf16_f32 v143, v210, v213
	v_cvt_pk_bf16_f32 v144, v198, v211
	v_cvt_pk_bf16_f32 v145, v197, v199
	v_cvt_pk_bf16_f32 v146, v64, v65
	v_cvt_pk_bf16_f32 v147, v66, v67
	v_cvt_pk_bf16_f32 v148, v68, v69
	v_cvt_pk_bf16_f32 v149, v70, v71
	v_cvt_pk_bf16_f32 v150, v72, v73
	v_cvt_pk_bf16_f32 v151, v74, v75
	v_cvt_pk_bf16_f32 v152, v76, v77
	v_cvt_pk_bf16_f32 v153, v78, v79
	v_permlane32_swap_b32_e32 v142, v144
	v_permlane32_swap_b32_e32 v143, v145
	v_permlane32_swap_b32_e32 v146, v148
	v_permlane32_swap_b32_e32 v147, v149
	v_permlane32_swap_b32_e32 v150, v152
	v_permlane32_swap_b32_e32 v151, v153
	s_add_i32 s2, s26, -1
	ds_read_b128 v[64:67], v170 offset:49152
	ds_read_b128 v[68:71], v170 offset:57344
	ds_read_b128 v[154:157], v171 offset:49152
	ds_read_b128 v[190:193], v171 offset:57344
	ds_read_b128 v[202:205], v172 offset:49152
	ds_read_b128 v[224:227], v172 offset:57344
	s_add_i32 s3, 0, 0x12000
	v_add_u32_e32 v189, s3, v178
	s_cmp_gt_u32 s2, s27
	s_cselect_b64 vcc, -1, 0
	s_waitcnt lgkmcnt(5)
	v_mfma_f32_32x32x16_bf16 v[80:95], v[64:67], v[126:129], 0
	s_waitcnt lgkmcnt(4)
	v_mfma_f32_32x32x16_bf16 v[64:79], v[68:71], v[126:129], 0
	s_waitcnt lgkmcnt(3)
	v_mfma_f32_32x32x16_bf16 v[80:95], v[154:157], v[122:125], v[80:95]
	ds_read_b128 v[154:157], v173 offset:49152
	s_waitcnt lgkmcnt(3)
	v_mfma_f32_32x32x16_bf16 v[64:79], v[190:193], v[122:125], v[64:79]
	ds_read_b128 v[190:193], v173 offset:57344
	s_waitcnt lgkmcnt(3)
	v_mfma_f32_32x32x16_bf16 v[80:95], v[202:205], v[118:121], v[80:95]
	ds_read_b128 v[202:205], v174 offset:49152
	s_waitcnt lgkmcnt(3)
	v_mfma_f32_32x32x16_bf16 v[64:79], v[224:227], v[118:121], v[64:79]
	ds_read_b128 v[224:227], v174 offset:57344
	s_waitcnt lgkmcnt(3)
	v_mfma_f32_32x32x16_bf16 v[80:95], v[154:157], v[114:117], v[80:95]
	ds_read_b128 v[154:157], v175 offset:49152
	s_waitcnt lgkmcnt(3)
	v_mfma_f32_32x32x16_bf16 v[64:79], v[190:193], v[114:117], v[64:79]
	ds_read_b128 v[190:193], v175 offset:57344
	s_waitcnt lgkmcnt(3)
	v_mfma_f32_32x32x16_bf16 v[80:95], v[202:205], v[110:113], v[80:95]
	ds_read_b128 v[202:205], v176 offset:49152
	s_waitcnt lgkmcnt(3)
	v_mfma_f32_32x32x16_bf16 v[64:79], v[224:227], v[110:113], v[64:79]
	ds_read_b128 v[224:227], v176 offset:57344
	s_waitcnt lgkmcnt(3)
	v_mfma_f32_32x32x16_bf16 v[80:95], v[154:157], v[106:109], v[80:95]
	ds_read_b128 v[154:157], v177 offset:49152
	s_waitcnt lgkmcnt(3)
	v_mfma_f32_32x32x16_bf16 v[64:79], v[190:193], v[106:109], v[64:79]
	ds_read_b128 v[190:193], v177 offset:57344
	s_waitcnt lgkmcnt(3)
	v_mfma_f32_32x32x16_bf16 v[80:95], v[202:205], v[102:105], v[80:95]
	s_waitcnt lgkmcnt(2)
	v_mfma_f32_32x32x16_bf16 v[64:79], v[224:227], v[102:105], v[64:79]
	s_waitcnt lgkmcnt(1)
	v_mfma_f32_32x32x16_bf16 v[80:95], v[154:157], v[98:101], v[80:95]
	s_waitcnt lgkmcnt(0)
	v_mfma_f32_32x32x16_bf16 v[64:79], v[190:193], v[98:101], v[64:79]
	ds_read_b128 v[154:157], v189
	ds_read_b128 v[190:193], v189 offset:4096
	ds_read_b128 v[202:205], v163
	s_waitcnt lgkmcnt(0)
	v_mfma_f32_32x32x16_bf16 v[80:95], v[154:157], v[202:205], v[80:95]
	v_mfma_f32_32x32x16_bf16 v[64:79], v[190:193], v[202:205], v[64:79]
	v_add_u32_e32 v190, s3, v180
	ds_read_b128 v[154:157], v190
	ds_read_b128 v[192:195], v190 offset:4096
	ds_read_b128 v[202:205], v163 offset:1024
	v_add_u32_e32 v191, s3, v182
	s_waitcnt lgkmcnt(0)
	v_mfma_f32_32x32x16_bf16 v[80:95], v[154:157], v[202:205], v[80:95]
	v_mfma_f32_32x32x16_bf16 v[64:79], v[192:195], v[202:205], v[64:79]
	ds_read_b128 v[154:157], v191
	ds_read_b128 v[192:195], v191 offset:4096
	ds_read_b128 v[202:205], v163 offset:2048
	s_waitcnt lgkmcnt(0)
	v_mfma_f32_32x32x16_bf16 v[80:95], v[154:157], v[202:205], v[80:95]
	v_mfma_f32_32x32x16_bf16 v[64:79], v[192:195], v[202:205], v[64:79]
	v_add_u32_e32 v192, s3, v184
	ds_read_b128 v[154:157], v192
	ds_read_b128 v[202:205], v192 offset:4096
	ds_read_b128 v[224:227], v163 offset:3072
	s_waitcnt lgkmcnt(0)
	v_mfma_f32_32x32x16_bf16 v[80:95], v[154:157], v[224:227], v[80:95]
	v_mfma_f32_32x32x16_bf16 v[64:79], v[202:205], v[224:227], v[64:79]
	s_nop 10
	v_cndmask_b32_e32 v240, v80, v208, vcc
	v_cndmask_b32_e32 v244, v64, v208, vcc
	v_cndmask_b32_e32 v245, v65, v208, vcc
	v_cndmask_b32_e32 v242, v66, v208, vcc
	v_cndmask_b32_e32 v243, v67, v208, vcc
	v_cndmask_b32_e32 v238, v68, v208, vcc
	v_cndmask_b32_e32 v239, v69, v208, vcc
	v_cndmask_b32_e32 v234, v70, v208, vcc
	v_cndmask_b32_e32 v235, v71, v208, vcc
	v_cndmask_b32_e32 v230, v72, v208, vcc
	v_cndmask_b32_e32 v231, v73, v208, vcc
	v_cndmask_b32_e32 v227, v74, v208, vcc
	v_cndmask_b32_e32 v228, v75, v208, vcc
	v_cndmask_b32_e32 v225, v76, v208, vcc
	v_cndmask_b32_e32 v195, v90, v208, vcc
	v_cndmask_b32_e32 v90, v77, v208, vcc
	v_cndmask_b32_e32 v223, v88, v208, vcc
	v_cndmask_b32_e32 v88, v78, v208, vcc
	v_cndmask_b32_e32 v224, v89, v208, vcc
	v_cndmask_b32_e32 v89, v79, v208, vcc
	v_cndmask_b32_e32 v226, v86, v208, vcc
	v_cndmask_b32_e32 v232, v84, v208, vcc
	v_cndmask_b32_e32 v233, v85, v208, vcc
	v_cndmask_b32_e32 v94, v94, v208, vcc
	v_cndmask_b32_e32 v95, v95, v208, vcc
	v_cndmask_b32_e32 v92, v92, v208, vcc
	v_cndmask_b32_e32 v93, v93, v208, vcc
	v_cndmask_b32_e32 v91, v91, v208, vcc
	v_cndmask_b32_e32 v229, v87, v208, vcc
	v_cndmask_b32_e32 v236, v82, v208, vcc
	v_cndmask_b32_e32 v237, v83, v208, vcc
	v_cndmask_b32_e32 v241, v81, v208, vcc
	v_mov_b32_e32 v193, v246
	v_mov_b32_e32 v194, v246
	v_cvt_pk_bf16_f32 v84, v220, v222
	v_cvt_pk_bf16_f32 v85, v218, v221
	v_cvt_pk_bf16_f32 v86, v216, v219
	v_cvt_pk_bf16_f32 v87, v215, v217
	s_nop 1
	v_permlane32_swap_b32_e32 v193, v194
	v_permlane32_swap_b32_e32 v84, v86
	v_permlane32_swap_b32_e32 v85, v87
	v_lshl_add_u64 v[138:139], v[134:135], 0, s[0:1]
	s_mov_b32 s3, 0x33080000
	v_add_co_u32_e32 v68, vcc, s3, v138
	s_mov_b32 s3, 0x330a0000
	s_nop 0
	v_addc_co_u32_e32 v69, vcc, 0, v139, vcc
	v_add_co_u32_e32 v72, vcc, s3, v138
	v_lshl_add_u64 v[140:141], v[132:133], 0, s[0:1]
	s_nop 0
	v_addc_co_u32_e32 v73, vcc, 0, v139, vcc
	s_mov_b32 s3, 0x2f804000
	global_load_dwordx4 v[64:67], v[68:69], off offset:256
	s_nop 0
	global_load_dwordx4 v[68:71], v[68:69], off
	s_nop 0
	global_load_dwordx4 v[76:79], v[72:73], off offset:256
	s_nop 0
	global_load_dwordx4 v[72:75], v[72:73], off
	v_add_co_u32_e32 v80, vcc, s3, v140
	s_nop 1
	v_addc_co_u32_e32 v81, vcc, 0, v141, vcc
	global_load_dwordx4 v[80:83], v[80:81], off
	ds_read_b64_tr_b16 v[154:155], v164 offset:0
	ds_read_b64_tr_b16 v[156:157], v164 offset:0x800
	ds_read_b64_tr_b16 v[196:197], v164 offset:0x1000
	ds_read_b64_tr_b16 v[198:199], v164 offset:0x1800
	ds_read_b64_tr_b16 v[202:203], v164 offset:0x2000
	ds_read_b64_tr_b16 v[204:205], v164 offset:0x2800
	ds_read_b64_tr_b16 v[210:211], v164 offset:0x3000
	ds_read_b64_tr_b16 v[212:213], v164 offset:0x3800
	s_waitcnt lgkmcnt(0)
	s_nop 0
	v_mfma_f32_32x32x16_bf16 v[0:15], v[84:87], v[154:157], v[0:15]
	ds_read_b64_tr_b16 v[154:155], v164 offset:0x200
	ds_read_b64_tr_b16 v[156:157], v164 offset:0xa00
	v_mfma_f32_32x32x16_bf16 v[0:15], v[142:145], v[196:199], v[0:15]
	ds_read_b64_tr_b16 v[196:197], v164 offset:0x1200
	ds_read_b64_tr_b16 v[198:199], v164 offset:0x1a00
	v_mfma_f32_32x32x16_bf16 v[0:15], v[146:149], v[202:205], v[0:15]
	ds_read_b64_tr_b16 v[202:203], v164 offset:0x2200
	ds_read_b64_tr_b16 v[204:205], v164 offset:0x2a00
	v_mfma_f32_32x32x16_bf16 v[0:15], v[150:153], v[210:213], v[0:15]
	ds_read_b64_tr_b16 v[210:211], v164 offset:0x3200
	ds_read_b64_tr_b16 v[212:213], v164 offset:0x3a00
	s_waitcnt lgkmcnt(0)
	v_mfma_f32_32x32x16_bf16 v[48:63], v[84:87], v[154:157], v[48:63]
	ds_read_b64_tr_b16 v[154:155], v164 offset:0x400
	ds_read_b64_tr_b16 v[156:157], v164 offset:0xc00
	v_mfma_f32_32x32x16_bf16 v[48:63], v[142:145], v[196:199], v[48:63]
	ds_read_b64_tr_b16 v[196:197], v164 offset:0x1400
	ds_read_b64_tr_b16 v[198:199], v164 offset:0x1c00
	v_mfma_f32_32x32x16_bf16 v[48:63], v[146:149], v[202:205], v[48:63]
	ds_read_b64_tr_b16 v[202:203], v164 offset:0x2400
	ds_read_b64_tr_b16 v[204:205], v164 offset:0x2c00
	v_mfma_f32_32x32x16_bf16 v[48:63], v[150:153], v[210:213], v[48:63]
	ds_read_b64_tr_b16 v[210:211], v164 offset:0x3400
	ds_read_b64_tr_b16 v[212:213], v164 offset:0x3c00
	s_waitcnt lgkmcnt(0)
	v_mfma_f32_32x32x16_bf16 v[32:47], v[84:87], v[154:157], v[32:47]
	ds_read_b64_tr_b16 v[154:155], v164 offset:0x600
	ds_read_b64_tr_b16 v[156:157], v164 offset:0xe00
	v_mfma_f32_32x32x16_bf16 v[32:47], v[142:145], v[196:199], v[32:47]
	ds_read_b64_tr_b16 v[196:197], v164 offset:0x1600
	ds_read_b64_tr_b16 v[198:199], v164 offset:0x1e00
	v_mfma_f32_32x32x16_bf16 v[32:47], v[146:149], v[202:205], v[32:47]
	ds_read_b64_tr_b16 v[202:203], v164 offset:0x2600
	ds_read_b64_tr_b16 v[204:205], v164 offset:0x2e00
	v_mfma_f32_32x32x16_bf16 v[32:47], v[150:153], v[210:213], v[32:47]
	ds_read_b64_tr_b16 v[210:211], v164 offset:0x3600
	ds_read_b64_tr_b16 v[212:213], v164 offset:0x3e00
	s_waitcnt lgkmcnt(0)
	v_mfma_f32_32x32x16_bf16 v[16:31], v[84:87], v[154:157], v[16:31]
	v_max_f32_e32 v84, v241, v241
	v_max_f32_e32 v85, v240, v240
	v_max_f32_e32 v84, v85, v84
	v_max3_f32 v84, v84, v236, v237
	v_max3_f32 v84, v84, v232, v233
	v_max3_f32 v84, v84, v226, v229
	v_max3_f32 v84, v84, v223, v224
	v_mfma_f32_32x32x16_bf16 v[16:31], v[142:145], v[196:199], v[16:31]
	v_max3_f32 v84, v84, v195, v91
	v_max3_f32 v84, v84, v92, v93
	v_max3_f32 v84, v84, v94, v95
	v_max3_f32 v84, v84, v244, v245
	v_max3_f32 v84, v84, v242, v243
	v_max3_f32 v84, v84, v238, v239
	v_max3_f32 v84, v84, v234, v235
	v_mfma_f32_32x32x16_bf16 v[16:31], v[146:149], v[202:205], v[16:31]
	v_max3_f32 v84, v84, v230, v231
	v_max3_f32 v84, v84, v227, v228
	v_max3_f32 v84, v84, v225, v90
	v_max3_f32 v84, v84, v88, v89
	v_mov_b32_e32 v85, v84
	s_nop 1
	v_permlane32_swap_b32_e32 v84, v85
	v_mfma_f32_32x32x16_bf16 v[16:31], v[150:153], v[210:213], v[16:31]
	v_max_f32_e32 v85, v85, v85
	v_max_f32_e32 v84, v84, v84
	v_max_f32_e32 v84, v84, v85
	v_sub_f32_e32 v85, v84, v165
	v_cmp_ge_f32_e32 vcc, s21, v85
	v_mov_b32_e32 v196, 1.0
	s_cmp_eq_u64 vcc, exec
	s_cbranch_scc0 .Latt1_750

.Latt1_743:
	v_mul_f32_e32 v136, 0xbdd53b94, v165
	v_fmamk_f32 v78, v94, 0x3dd53b94, v136
	v_fmamk_f32 v74, v195, 0x3dd53b94, v136
	v_exp_f32_e32 v195, v78
	v_fmamk_f32 v64, v240, 0x3dd53b94, v136
	v_fmamk_f32 v65, v241, 0x3dd53b94, v136
	v_fmamk_f32 v66, v236, 0x3dd53b94, v136
	v_fmamk_f32 v67, v237, 0x3dd53b94, v136
	v_fmamk_f32 v68, v232, 0x3dd53b94, v136
	v_fmamk_f32 v69, v233, 0x3dd53b94, v136
	v_fmamk_f32 v70, v226, 0x3dd53b94, v136
	v_fmamk_f32 v71, v229, 0x3dd53b94, v136
	v_fmamk_f32 v72, v223, 0x3dd53b94, v136
	v_fmamk_f32 v73, v224, 0x3dd53b94, v136
	v_fmamk_f32 v75, v91, 0x3dd53b94, v136
	v_fmamk_f32 v76, v92, 0x3dd53b94, v136
	v_fmamk_f32 v77, v93, 0x3dd53b94, v136
	v_fmamk_f32 v79, v95, 0x3dd53b94, v136
	v_fmamk_f32 v223, v244, 0x3dd53b94, v136
	v_fmamk_f32 v224, v245, 0x3dd53b94, v136
	v_fmamk_f32 v236, v242, 0x3dd53b94, v136
	v_fmamk_f32 v237, v243, 0x3dd53b94, v136
	v_fmamk_f32 v238, v238, 0x3dd53b94, v136
	v_fmamk_f32 v239, v239, 0x3dd53b94, v136
	v_fmamk_f32 v240, v234, 0x3dd53b94, v136
	v_fmamk_f32 v241, v235, 0x3dd53b94, v136
	v_fmamk_f32 v242, v230, 0x3dd53b94, v136
	v_fmamk_f32 v243, v231, 0x3dd53b94, v136
	v_fmamk_f32 v244, v227, 0x3dd53b94, v136
	v_fmamk_f32 v245, v228, 0x3dd53b94, v136
	v_fmamk_f32 v246, v225, 0x3dd53b94, v136
	v_exp_f32_e32 v233, v64
	v_exp_f32_e32 v235, v65
	v_exp_f32_e32 v231, v66
	v_exp_f32_e32 v234, v67
	v_exp_f32_e32 v229, v68
	v_exp_f32_e32 v232, v69
	v_exp_f32_e32 v228, v70
	v_exp_f32_e32 v230, v71
	v_exp_f32_e32 v225, v72
	v_exp_f32_e32 v227, v73
	v_exp_f32_e32 v221, v74
	v_exp_f32_e32 v226, v75
	v_exp_f32_e32 v219, v76
	v_exp_f32_e32 v222, v77
	v_exp_f32_e32 v220, v79
	v_fmamk_f32 v247, v90, 0x3dd53b94, v136
	v_fmamk_f32 v248, v88, 0x3dd53b94, v136
	v_fmamk_f32 v202, v89, 0x3dd53b94, v136
	s_waitcnt lgkmcnt(0)
	s_barrier
	v_add_f32_e32 v80, 0, v233
	v_add_f32_e32 v80, v235, v80
	v_add_f32_e32 v80, v231, v80
	v_add_f32_e32 v80, v234, v80
	v_add_f32_e32 v80, v229, v80
	v_add_f32_e32 v80, v232, v80
	v_add_f32_e32 v80, v228, v80
	v_add_f32_e32 v80, v230, v80
	v_add_f32_e32 v80, v225, v80
	v_add_f32_e32 v80, v227, v80
	v_add_f32_e32 v80, v221, v80
	v_add_f32_e32 v80, v226, v80
	v_exp_f32_e32 v64, v223
	v_add_f32_e32 v80, v219, v80
	v_exp_f32_e32 v65, v224
	v_add_f32_e32 v80, v222, v80
	v_exp_f32_e32 v66, v236
	v_add_f32_e32 v80, v195, v80
	v_exp_f32_e32 v67, v237
	v_add_f32_e32 v80, v220, v80
	v_exp_f32_e32 v68, v238
	v_add_f32_e32 v80, v64, v80
	v_exp_f32_e32 v69, v239
	v_add_f32_e32 v80, v65, v80
	v_exp_f32_e32 v70, v240
	v_add_f32_e32 v80, v66, v80
	v_exp_f32_e32 v71, v241
	v_add_f32_e32 v80, v67, v80
	v_exp_f32_e32 v72, v242
	v_add_f32_e32 v80, v68, v80
	v_exp_f32_e32 v73, v243
	v_add_f32_e32 v80, v69, v80
	v_exp_f32_e32 v74, v244
	v_add_f32_e32 v80, v70, v80
	v_exp_f32_e32 v75, v245
	v_add_f32_e32 v80, v71, v80
	v_exp_f32_e32 v76, v246
	v_add_f32_e32 v80, v72, v80
	v_exp_f32_e32 v77, v247
	v_add_f32_e32 v80, v73, v80
	v_exp_f32_e32 v78, v248
	v_add_f32_e32 v80, v74, v80
	v_exp_f32_e32 v79, v202
	v_add_f32_e32 v80, v75, v80
	v_add_f32_e32 v80, v76, v80
	v_add_f32_e32 v80, v77, v80
	v_add_f32_e32 v80, v78, v80
	v_add_f32_e32 v223, v79, v80
	v_mov_b32_e32 v224, v223
	v_cvt_pk_bf16_f32 v247, v229, v232
	v_cvt_pk_bf16_f32 v248, v228, v230
	v_cvt_pk_bf16_f32 v154, v225, v227
	v_cvt_pk_bf16_f32 v155, v221, v226
	v_cvt_pk_bf16_f32 v156, v219, v222
	v_cvt_pk_bf16_f32 v157, v195, v220
	v_cvt_pk_bf16_f32 v202, v64, v65
	v_cvt_pk_bf16_f32 v203, v66, v67
	v_cvt_pk_bf16_f32 v204, v68, v69
	v_cvt_pk_bf16_f32 v205, v70, v71
	v_cvt_pk_bf16_f32 v226, v72, v73
	v_cvt_pk_bf16_f32 v227, v74, v75
	v_cvt_pk_bf16_f32 v228, v76, v77
	v_cvt_pk_bf16_f32 v229, v78, v79
	v_permlane32_swap_b32_e32 v154, v156
	v_permlane32_swap_b32_e32 v155, v157
	v_permlane32_swap_b32_e32 v202, v204
	v_permlane32_swap_b32_e32 v203, v205
	v_permlane32_swap_b32_e32 v226, v228
	v_permlane32_swap_b32_e32 v227, v229
	v_permlane32_swap_b32_e32 v223, v224
	ds_read_b128 v[64:67], v170 offset:32768
	ds_read_b128 v[68:71], v170 offset:40960
	ds_read_b128 v[142:145], v171 offset:32768
	ds_read_b128 v[146:149], v171 offset:40960
	ds_read_b128 v[150:153], v172 offset:32768
	s_cmp_lt_u32 s2, s27
	s_cselect_b64 vcc, -1, 0
	s_waitcnt lgkmcnt(4)
	v_mfma_f32_32x32x16_bf16 v[80:95], v[64:67], v[126:129], 0
	s_waitcnt lgkmcnt(3)
	v_mfma_f32_32x32x16_bf16 v[64:79], v[68:71], v[126:129], 0
	s_waitcnt lgkmcnt(2)
	v_mfma_f32_32x32x16_bf16 v[80:95], v[142:145], v[122:125], v[80:95]
	ds_read_b128 v[142:145], v172 offset:40960
	s_waitcnt lgkmcnt(2)
	v_mfma_f32_32x32x16_bf16 v[64:79], v[146:149], v[122:125], v[64:79]
	ds_read_b128 v[146:149], v173 offset:32768
	s_waitcnt lgkmcnt(2)
	v_mfma_f32_32x32x16_bf16 v[80:95], v[150:153], v[118:121], v[80:95]
	ds_read_b128 v[150:153], v173 offset:40960
	s_waitcnt lgkmcnt(2)
	v_mfma_f32_32x32x16_bf16 v[64:79], v[142:145], v[118:121], v[64:79]
	ds_read_b128 v[142:145], v174 offset:32768
	s_waitcnt lgkmcnt(2)
	v_mfma_f32_32x32x16_bf16 v[80:95], v[146:149], v[114:117], v[80:95]
	ds_read_b128 v[146:149], v174 offset:40960
	s_waitcnt lgkmcnt(2)
	v_mfma_f32_32x32x16_bf16 v[64:79], v[150:153], v[114:117], v[64:79]
	ds_read_b128 v[150:153], v175 offset:32768
	s_waitcnt lgkmcnt(2)
	v_mfma_f32_32x32x16_bf16 v[80:95], v[142:145], v[110:113], v[80:95]
	ds_read_b128 v[142:145], v175 offset:40960
	s_waitcnt lgkmcnt(2)
	v_mfma_f32_32x32x16_bf16 v[64:79], v[146:149], v[110:113], v[64:79]
	ds_read_b128 v[146:149], v176 offset:32768
	s_waitcnt lgkmcnt(2)
	v_mfma_f32_32x32x16_bf16 v[80:95], v[150:153], v[106:109], v[80:95]
	ds_read_b128 v[150:153], v176 offset:40960
	s_waitcnt lgkmcnt(2)
	v_mfma_f32_32x32x16_bf16 v[64:79], v[142:145], v[106:109], v[64:79]
	ds_read_b128 v[142:145], v177 offset:32768
	s_waitcnt lgkmcnt(2)
	v_mfma_f32_32x32x16_bf16 v[80:95], v[146:149], v[102:105], v[80:95]
	ds_read_b128 v[146:149], v177 offset:40960
	s_waitcnt lgkmcnt(2)
	v_mfma_f32_32x32x16_bf16 v[64:79], v[150:153], v[102:105], v[64:79]
	s_waitcnt lgkmcnt(1)
	v_mfma_f32_32x32x16_bf16 v[80:95], v[142:145], v[98:101], v[80:95]
	s_waitcnt lgkmcnt(0)
	v_mfma_f32_32x32x16_bf16 v[64:79], v[146:149], v[98:101], v[64:79]
	ds_read_b128 v[142:145], v179
	ds_read_b128 v[146:149], v179 offset:4096
	ds_read_b128 v[150:153], v163
	s_waitcnt lgkmcnt(0)
	v_mfma_f32_32x32x16_bf16 v[80:95], v[142:145], v[150:153], v[80:95]
	v_mfma_f32_32x32x16_bf16 v[64:79], v[146:149], v[150:153], v[64:79]
	ds_read_b128 v[142:145], v181
	ds_read_b128 v[146:149], v181 offset:4096
	ds_read_b128 v[150:153], v163 offset:1024
	s_waitcnt lgkmcnt(0)
	v_mfma_f32_32x32x16_bf16 v[80:95], v[142:145], v[150:153], v[80:95]
	v_mfma_f32_32x32x16_bf16 v[64:79], v[146:149], v[150:153], v[64:79]
	ds_read_b128 v[142:145], v183
	ds_read_b128 v[146:149], v183 offset:4096
	ds_read_b128 v[150:153], v163 offset:2048
	s_waitcnt lgkmcnt(0)
	v_mfma_f32_32x32x16_bf16 v[80:95], v[142:145], v[150:153], v[80:95]
	v_mfma_f32_32x32x16_bf16 v[64:79], v[146:149], v[150:153], v[64:79]
	ds_read_b128 v[142:145], v185
	ds_read_b128 v[146:149], v185 offset:4096
	ds_read_b128 v[150:153], v163 offset:3072
	s_waitcnt lgkmcnt(0)
	v_mfma_f32_32x32x16_bf16 v[80:95], v[142:145], v[150:153], v[80:95]
	v_mfma_f32_32x32x16_bf16 v[64:79], v[146:149], v[150:153], v[64:79]
	s_nop 10
	v_cndmask_b32_e32 v218, v208, v80, vcc
	v_cndmask_b32_e32 v148, v208, v64, vcc
	v_cndmask_b32_e32 v149, v208, v65, vcc
	v_cndmask_b32_e32 v146, v208, v66, vcc
	v_cndmask_b32_e32 v147, v208, v67, vcc
	v_cndmask_b32_e32 v144, v208, v68, vcc
	v_cndmask_b32_e32 v145, v208, v69, vcc
	v_cndmask_b32_e32 v142, v208, v70, vcc
	v_cndmask_b32_e32 v143, v208, v71, vcc
	v_cndmask_b32_e32 v151, v208, v94, vcc
	v_cndmask_b32_e32 v94, v208, v72, vcc
	v_cndmask_b32_e32 v150, v208, v95, vcc
	v_cndmask_b32_e32 v95, v208, v73, vcc
	v_cndmask_b32_e32 v153, v208, v92, vcc
	v_cndmask_b32_e32 v92, v208, v74, vcc
	v_cndmask_b32_e32 v152, v208, v93, vcc
	v_cndmask_b32_e32 v93, v208, v75, vcc
	v_cndmask_b32_e32 v198, v208, v90, vcc
	v_cndmask_b32_e32 v90, v208, v76, vcc
	v_cndmask_b32_e32 v197, v208, v91, vcc
	v_cndmask_b32_e32 v91, v208, v77, vcc
	v_cndmask_b32_e32 v210, v208, v88, vcc
	v_cndmask_b32_e32 v88, v208, v78, vcc
	v_cndmask_b32_e32 v199, v208, v89, vcc
	v_cndmask_b32_e32 v89, v208, v79, vcc
	v_cndmask_b32_e32 v212, v208, v86, vcc
	v_cndmask_b32_e32 v213, v208, v85, vcc
	v_cndmask_b32_e32 v214, v208, v84, vcc
	v_cndmask_b32_e32 v211, v208, v87, vcc
	v_cndmask_b32_e32 v215, v208, v83, vcc
	v_cndmask_b32_e32 v216, v208, v82, vcc
	v_cndmask_b32_e32 v217, v208, v81, vcc
	v_cvt_pk_bf16_f32 v84, v233, v235
	v_cvt_pk_bf16_f32 v85, v231, v234
	v_mov_b32_e32 v86, v247
	v_mov_b32_e32 v87, v248
	s_nop 1
	v_permlane32_swap_b32_e32 v84, v86
	v_permlane32_swap_b32_e32 v85, v87
	v_add_co_u32_e32 v68, vcc, s22, v138
	s_nop 1
	v_addc_co_u32_e32 v69, vcc, 0, v139, vcc
	v_add_co_u32_e32 v72, vcc, s23, v138
	s_nop 1
	v_addc_co_u32_e32 v73, vcc, 0, v139, vcc
	global_load_dwordx4 v[64:67], v[68:69], off offset:256
	s_nop 0
	global_load_dwordx4 v[68:71], v[68:69], off
	s_nop 0
	global_load_dwordx4 v[76:79], v[72:73], off offset:256
	s_nop 0
	global_load_dwordx4 v[72:75], v[72:73], off
	v_add_co_u32_e32 v80, vcc, s29, v140
	s_nop 1
	v_addc_co_u32_e32 v81, vcc, 0, v141, vcc
	global_load_dwordx4 v[80:83], v[80:81], off
	ds_read_b64_tr_b16 v[138:139], v162 offset:0
	ds_read_b64_tr_b16 v[140:141], v162 offset:0x800
	ds_read_b64_tr_b16 v[230:231], v162 offset:0x1000
	ds_read_b64_tr_b16 v[232:233], v162 offset:0x1800
	ds_read_b64_tr_b16 v[234:235], v162 offset:0x2000
	ds_read_b64_tr_b16 v[236:237], v162 offset:0x2800
	ds_read_b64_tr_b16 v[238:239], v162 offset:0x3000
	ds_read_b64_tr_b16 v[240:241], v162 offset:0x3800
	s_waitcnt lgkmcnt(0)
	s_nop 0
	v_mfma_f32_32x32x16_bf16 v[0:15], v[84:87], v[138:141], v[0:15]
	ds_read_b64_tr_b16 v[138:139], v162 offset:0x200
	ds_read_b64_tr_b16 v[140:141], v162 offset:0xa00
	v_mfma_f32_32x32x16_bf16 v[0:15], v[154:157], v[230:233], v[0:15]
	ds_read_b64_tr_b16 v[230:231], v162 offset:0x1200
	ds_read_b64_tr_b16 v[232:233], v162 offset:0x1a00
	v_mfma_f32_32x32x16_bf16 v[0:15], v[202:205], v[234:237], v[0:15]
	ds_read_b64_tr_b16 v[234:235], v162 offset:0x2200
	ds_read_b64_tr_b16 v[236:237], v162 offset:0x2a00
	v_mfma_f32_32x32x16_bf16 v[0:15], v[226:229], v[238:241], v[0:15]
	ds_read_b64_tr_b16 v[238:239], v162 offset:0x3200
	ds_read_b64_tr_b16 v[240:241], v162 offset:0x3a00
	s_waitcnt lgkmcnt(0)
	v_mfma_f32_32x32x16_bf16 v[48:63], v[84:87], v[138:141], v[48:63]
	ds_read_b64_tr_b16 v[138:139], v162 offset:0x400
	ds_read_b64_tr_b16 v[140:141], v162 offset:0xc00
	v_mfma_f32_32x32x16_bf16 v[48:63], v[154:157], v[230:233], v[48:63]
	ds_read_b64_tr_b16 v[230:231], v162 offset:0x1400
	ds_read_b64_tr_b16 v[232:233], v162 offset:0x1c00
	v_mfma_f32_32x32x16_bf16 v[48:63], v[202:205], v[234:237], v[48:63]
	ds_read_b64_tr_b16 v[234:235], v162 offset:0x2400
	ds_read_b64_tr_b16 v[236:237], v162 offset:0x2c00
	v_mfma_f32_32x32x16_bf16 v[48:63], v[226:229], v[238:241], v[48:63]
	ds_read_b64_tr_b16 v[238:239], v162 offset:0x3400
	ds_read_b64_tr_b16 v[240:241], v162 offset:0x3c00
	s_waitcnt lgkmcnt(0)
	v_mfma_f32_32x32x16_bf16 v[32:47], v[84:87], v[138:141], v[32:47]
	ds_read_b64_tr_b16 v[138:139], v162 offset:0x600
	ds_read_b64_tr_b16 v[140:141], v162 offset:0xe00
	v_mfma_f32_32x32x16_bf16 v[32:47], v[154:157], v[230:233], v[32:47]
	ds_read_b64_tr_b16 v[230:231], v162 offset:0x1600
	ds_read_b64_tr_b16 v[232:233], v162 offset:0x1e00
	v_mfma_f32_32x32x16_bf16 v[32:47], v[202:205], v[234:237], v[32:47]
	ds_read_b64_tr_b16 v[234:235], v162 offset:0x2600
	ds_read_b64_tr_b16 v[236:237], v162 offset:0x2e00
	v_mfma_f32_32x32x16_bf16 v[32:47], v[226:229], v[238:241], v[32:47]
	ds_read_b64_tr_b16 v[238:239], v162 offset:0x3600
	ds_read_b64_tr_b16 v[240:241], v162 offset:0x3e00
	s_waitcnt lgkmcnt(0)
	v_mfma_f32_32x32x16_bf16 v[16:31], v[84:87], v[138:141], v[16:31]
	v_max_f32_e32 v84, v217, v217
	v_max_f32_e32 v85, v218, v218
	v_max_f32_e32 v84, v85, v84
	v_max3_f32 v84, v84, v216, v215
	v_max3_f32 v84, v84, v214, v213
	v_max3_f32 v84, v84, v212, v211
	v_max3_f32 v84, v84, v210, v199
	v_mfma_f32_32x32x16_bf16 v[16:31], v[154:157], v[230:233], v[16:31]
	v_max3_f32 v84, v84, v198, v197
	v_max3_f32 v84, v84, v153, v152
	v_max3_f32 v84, v84, v151, v150
	v_max3_f32 v84, v84, v148, v149
	v_max3_f32 v84, v84, v146, v147
	v_max3_f32 v84, v84, v144, v145
	v_max3_f32 v84, v84, v142, v143
	v_mfma_f32_32x32x16_bf16 v[16:31], v[202:205], v[234:237], v[16:31]
	v_max3_f32 v84, v84, v94, v95
	v_max3_f32 v84, v84, v92, v93
	v_max3_f32 v84, v84, v90, v91
	v_max3_f32 v84, v84, v88, v89
	v_mov_b32_e32 v85, v84
	s_nop 1
	v_permlane32_swap_b32_e32 v84, v85
	v_mfma_f32_32x32x16_bf16 v[16:31], v[226:229], v[238:241], v[16:31]
	v_max_f32_e32 v85, v85, v85
	v_max_f32_e32 v84, v84, v84
	v_max_f32_e32 v84, v84, v85
	v_sub_f32_e32 v85, v84, v165
	v_cmp_ge_f32_e32 vcc, s21, v85
	v_mov_b32_e32 v195, 1.0
	s_cmp_eq_u64 vcc, exec
	s_cbranch_scc0 .Latt1_751
